# combined tile-transition edits on the best version: restore barrier at K-loop entry + no store-drain vmcnt(0) before the next tile in P5/P9/P10
# baseline (speedup 1.0000x reference)
.LBB0_985:
	s_ashr_i32 s17, s16, 31
	s_lshl_b64 s[18:19], s[16:17], 19
	s_add_u32 s18, s52, s18
	s_addc_u32 s19, s53, s19
	s_and_b64 s[20:21], s[0:1], exec
	s_cselect_b32 s17, s19, s25
	s_cselect_b32 s45, s18, s24
	s_ashr_i32 s15, s14, 31
	s_lshl_b64 s[20:21], s[14:15], 19
	s_add_u32 s20, s58, s20
	s_addc_u32 s21, s59, s21
	s_and_b64 s[28:29], s[0:1], exec
	s_cselect_b32 s15, s21, s27
	s_cselect_b32 s46, s20, s26
	s_add_u32 s24, s24, 0x40080
	s_addc_u32 s25, s25, 0
	s_add_u32 s47, s26, 0x100
	v_mov_b32_e32 v2, 0
	s_addc_u32 s48, s27, 0
	s_mov_b32 s49, -2
	v_mov_b32_e32 v3, v2
	v_mov_b32_e32 v4, v2
	v_mov_b32_e32 v5, v2
	v_mov_b32_e32 v6, v2
	v_mov_b32_e32 v7, v2
	v_mov_b32_e32 v8, v2
	v_mov_b32_e32 v9, v2
	v_mov_b32_e32 v18, v2
	v_mov_b32_e32 v19, v2
	v_mov_b32_e32 v20, v2
	v_mov_b32_e32 v21, v2
	v_mov_b32_e32 v22, v2
	v_mov_b32_e32 v23, v2
	v_mov_b32_e32 v24, v2
	v_mov_b32_e32 v25, v2
	v_mov_b32_e32 v34, v2
	v_mov_b32_e32 v35, v2
	v_mov_b32_e32 v36, v2
	v_mov_b32_e32 v37, v2
	v_mov_b32_e32 v38, v2
	v_mov_b32_e32 v39, v2
	v_mov_b32_e32 v40, v2
	v_mov_b32_e32 v41, v2
	v_mov_b32_e32 v50, v2
	v_mov_b32_e32 v51, v2
	v_mov_b32_e32 v52, v2
	v_mov_b32_e32 v53, v2
	v_mov_b32_e32 v54, v2
	v_mov_b32_e32 v55, v2
	v_mov_b32_e32 v56, v2
	v_mov_b32_e32 v57, v2
	v_mov_b32_e32 v10, v2
	v_mov_b32_e32 v11, v2
	v_mov_b32_e32 v12, v2
	v_mov_b32_e32 v13, v2
	v_mov_b32_e32 v14, v2
	v_mov_b32_e32 v15, v2
	v_mov_b32_e32 v16, v2
	v_mov_b32_e32 v17, v2
	v_mov_b32_e32 v26, v2
	v_mov_b32_e32 v27, v2
	v_mov_b32_e32 v28, v2
	v_mov_b32_e32 v29, v2
	v_mov_b32_e32 v30, v2
	v_mov_b32_e32 v31, v2
	v_mov_b32_e32 v32, v2
	v_mov_b32_e32 v33, v2
	v_mov_b32_e32 v42, v2
	v_mov_b32_e32 v43, v2
	v_mov_b32_e32 v44, v2
	v_mov_b32_e32 v45, v2
	v_mov_b32_e32 v46, v2
	v_mov_b32_e32 v47, v2
	v_mov_b32_e32 v48, v2
	v_mov_b32_e32 v49, v2
	v_mov_b32_e32 v58, v2
	v_mov_b32_e32 v59, v2
	v_mov_b32_e32 v60, v2
	v_mov_b32_e32 v61, v2
	v_mov_b32_e32 v62, v2
	v_mov_b32_e32 v63, v2
	v_mov_b32_e32 v64, v2
	v_mov_b32_e32 v65, v2
	v_mov_b32_e32 v66, v2
	v_mov_b32_e32 v67, v2
	v_mov_b32_e32 v68, v2
	v_mov_b32_e32 v69, v2
	v_mov_b32_e32 v70, v2
	v_mov_b32_e32 v71, v2
	v_mov_b32_e32 v72, v2
	v_mov_b32_e32 v73, v2
	v_mov_b32_e32 v82, v2
	v_mov_b32_e32 v83, v2
	v_mov_b32_e32 v84, v2
	v_mov_b32_e32 v85, v2
	v_mov_b32_e32 v86, v2
	v_mov_b32_e32 v87, v2
	v_mov_b32_e32 v88, v2
	v_mov_b32_e32 v89, v2
	v_mov_b32_e32 v98, v2
	v_mov_b32_e32 v99, v2
	v_mov_b32_e32 v100, v2
	v_mov_b32_e32 v101, v2
	v_mov_b32_e32 v102, v2
	v_mov_b32_e32 v103, v2
	v_mov_b32_e32 v104, v2
	v_mov_b32_e32 v105, v2
	v_mov_b32_e32 v114, v2
	v_mov_b32_e32 v115, v2
	v_mov_b32_e32 v116, v2
	v_mov_b32_e32 v117, v2
	v_mov_b32_e32 v118, v2
	v_mov_b32_e32 v119, v2
	v_mov_b32_e32 v120, v2
	v_mov_b32_e32 v121, v2
	v_mov_b32_e32 v74, v2
	v_mov_b32_e32 v75, v2
	v_mov_b32_e32 v76, v2
	v_mov_b32_e32 v77, v2
	v_mov_b32_e32 v78, v2
	v_mov_b32_e32 v79, v2
	v_mov_b32_e32 v80, v2
	v_mov_b32_e32 v81, v2
	v_mov_b32_e32 v90, v2
	v_mov_b32_e32 v91, v2
	v_mov_b32_e32 v92, v2
	v_mov_b32_e32 v93, v2
	v_mov_b32_e32 v94, v2
	v_mov_b32_e32 v95, v2
	v_mov_b32_e32 v96, v2
	v_mov_b32_e32 v97, v2
	v_mov_b32_e32 v106, v2
	v_mov_b32_e32 v107, v2
	v_mov_b32_e32 v108, v2
	v_mov_b32_e32 v109, v2
	v_mov_b32_e32 v110, v2
	v_mov_b32_e32 v111, v2
	v_mov_b32_e32 v112, v2
	v_mov_b32_e32 v113, v2
	v_mov_b32_e32 v122, v2
	v_mov_b32_e32 v123, v2
	v_mov_b32_e32 v124, v2
	v_mov_b32_e32 v125, v2
	v_mov_b32_e32 v126, v2
	v_mov_b32_e32 v127, v2
	v_mov_b32_e32 v128, v2
	v_mov_b32_e32 v129, v2
	s_cmp_lt_u32 s37, 2
	s_cbranch_scc1 .Lp5_norestore
	s_andn2_b64 vcc, exec, s[2:3]
	s_cbranch_vccnz .Lp5_norestore
	s_barrier

.LBB0_1207:
	s_ashr_i32 s21, s20, 31
	s_lshl_b64 s[22:23], s[20:21], 20
	s_add_u32 s22, s52, s22
	s_addc_u32 s23, s53, s23
	s_and_b64 s[24:25], s[0:1], exec
	s_cselect_b32 s21, s23, s27
	s_cselect_b32 s50, s22, s26
	s_ashr_i32 s19, s18, 31
	s_lshl_b64 s[24:25], s[18:19], 20
	v_readlane_b32 s30, v240, 23
	v_readlane_b32 s31, v240, 24
	s_add_u32 s24, s30, s24
	s_addc_u32 s25, s31, s25
	s_and_b64 s[30:31], s[0:1], exec
	s_cselect_b32 s19, s25, s29
	s_cselect_b32 s51, s24, s28
	s_add_u32 s26, s26, 0x80080
	s_addc_u32 s27, s27, 0
	s_add_u32 s56, s28, 0x100
	v_mov_b32_e32 v2, 0
	s_addc_u32 s57, s29, 0
	s_mov_b32 s58, -2
	v_mov_b32_e32 v3, v2
	v_mov_b32_e32 v4, v2
	v_mov_b32_e32 v5, v2
	v_mov_b32_e32 v6, v2
	v_mov_b32_e32 v7, v2
	v_mov_b32_e32 v8, v2
	v_mov_b32_e32 v9, v2
	v_mov_b32_e32 v18, v2
	v_mov_b32_e32 v19, v2
	v_mov_b32_e32 v20, v2
	v_mov_b32_e32 v21, v2
	v_mov_b32_e32 v22, v2
	v_mov_b32_e32 v23, v2
	v_mov_b32_e32 v24, v2
	v_mov_b32_e32 v25, v2
	v_mov_b32_e32 v34, v2
	v_mov_b32_e32 v35, v2
	v_mov_b32_e32 v36, v2
	v_mov_b32_e32 v37, v2
	v_mov_b32_e32 v38, v2
	v_mov_b32_e32 v39, v2
	v_mov_b32_e32 v40, v2
	v_mov_b32_e32 v41, v2
	v_mov_b32_e32 v50, v2
	v_mov_b32_e32 v51, v2
	v_mov_b32_e32 v52, v2
	v_mov_b32_e32 v53, v2
	v_mov_b32_e32 v54, v2
	v_mov_b32_e32 v55, v2
	v_mov_b32_e32 v56, v2
	v_mov_b32_e32 v57, v2
	v_mov_b32_e32 v10, v2
	v_mov_b32_e32 v11, v2
	v_mov_b32_e32 v12, v2
	v_mov_b32_e32 v13, v2
	v_mov_b32_e32 v14, v2
	v_mov_b32_e32 v15, v2
	v_mov_b32_e32 v16, v2
	v_mov_b32_e32 v17, v2
	v_mov_b32_e32 v26, v2
	v_mov_b32_e32 v27, v2
	v_mov_b32_e32 v28, v2
	v_mov_b32_e32 v29, v2
	v_mov_b32_e32 v30, v2
	v_mov_b32_e32 v31, v2
	v_mov_b32_e32 v32, v2
	v_mov_b32_e32 v33, v2
	v_mov_b32_e32 v42, v2
	v_mov_b32_e32 v43, v2
	v_mov_b32_e32 v44, v2
	v_mov_b32_e32 v45, v2
	v_mov_b32_e32 v46, v2
	v_mov_b32_e32 v47, v2
	v_mov_b32_e32 v48, v2
	v_mov_b32_e32 v49, v2
	v_mov_b32_e32 v58, v2
	v_mov_b32_e32 v59, v2
	v_mov_b32_e32 v60, v2
	v_mov_b32_e32 v61, v2
	v_mov_b32_e32 v62, v2
	v_mov_b32_e32 v63, v2
	v_mov_b32_e32 v64, v2
	v_mov_b32_e32 v65, v2
	v_mov_b32_e32 v66, v2
	v_mov_b32_e32 v67, v2
	v_mov_b32_e32 v68, v2
	v_mov_b32_e32 v69, v2
	v_mov_b32_e32 v70, v2
	v_mov_b32_e32 v71, v2
	v_mov_b32_e32 v72, v2
	v_mov_b32_e32 v73, v2
	v_mov_b32_e32 v82, v2
	v_mov_b32_e32 v83, v2
	v_mov_b32_e32 v84, v2
	v_mov_b32_e32 v85, v2
	v_mov_b32_e32 v86, v2
	v_mov_b32_e32 v87, v2
	v_mov_b32_e32 v88, v2
	v_mov_b32_e32 v89, v2
	v_mov_b32_e32 v114, v2
	v_mov_b32_e32 v115, v2
	v_mov_b32_e32 v116, v2
	v_mov_b32_e32 v117, v2
	v_mov_b32_e32 v118, v2
	v_mov_b32_e32 v119, v2
	v_mov_b32_e32 v120, v2
	v_mov_b32_e32 v121, v2
	v_mov_b32_e32 v130, v2
	v_mov_b32_e32 v131, v2
	v_mov_b32_e32 v132, v2
	v_mov_b32_e32 v133, v2
	v_mov_b32_e32 v134, v2
	v_mov_b32_e32 v135, v2
	v_mov_b32_e32 v136, v2
	v_mov_b32_e32 v137, v2
	v_mov_b32_e32 v74, v2
	v_mov_b32_e32 v75, v2
	v_mov_b32_e32 v76, v2
	v_mov_b32_e32 v77, v2
	v_mov_b32_e32 v78, v2
	v_mov_b32_e32 v79, v2
	v_mov_b32_e32 v80, v2
	v_mov_b32_e32 v81, v2
	v_mov_b32_e32 v90, v2
	v_mov_b32_e32 v91, v2
	v_mov_b32_e32 v92, v2
	v_mov_b32_e32 v93, v2
	v_mov_b32_e32 v94, v2
	v_mov_b32_e32 v95, v2
	v_mov_b32_e32 v96, v2
	v_mov_b32_e32 v97, v2
	v_mov_b32_e32 v122, v2
	v_mov_b32_e32 v123, v2
	v_mov_b32_e32 v124, v2
	v_mov_b32_e32 v125, v2
	v_mov_b32_e32 v126, v2
	v_mov_b32_e32 v127, v2
	v_mov_b32_e32 v128, v2
	v_mov_b32_e32 v129, v2
	v_mov_b32_e32 v138, v2
	v_mov_b32_e32 v139, v2
	v_mov_b32_e32 v140, v2
	v_mov_b32_e32 v141, v2
	v_mov_b32_e32 v142, v2
	v_mov_b32_e32 v143, v2
	v_mov_b32_e32 v144, v2
	v_mov_b32_e32 v145, v2
	s_cmp_lt_u32 s40, 2
	s_cbranch_scc1 .Lp9_norestore
	s_andn2_b64 vcc, exec, s[2:3]
	s_cbranch_vccnz .Lp9_norestore
	s_barrier

.LBB0_1283:
	s_add_u32 s58, s28, 0x100
	v_mov_b32_e32 v2, 0
	s_addc_u32 s59, s29, 0
	s_mov_b32 s60, -2
	v_mov_b32_e32 v3, v2
	v_mov_b32_e32 v4, v2
	v_mov_b32_e32 v5, v2
	v_mov_b32_e32 v6, v2
	v_mov_b32_e32 v7, v2
	v_mov_b32_e32 v8, v2
	v_mov_b32_e32 v9, v2
	v_mov_b32_e32 v18, v2
	v_mov_b32_e32 v19, v2
	v_mov_b32_e32 v20, v2
	v_mov_b32_e32 v21, v2
	v_mov_b32_e32 v22, v2
	v_mov_b32_e32 v23, v2
	v_mov_b32_e32 v24, v2
	v_mov_b32_e32 v25, v2
	v_mov_b32_e32 v34, v2
	v_mov_b32_e32 v35, v2
	v_mov_b32_e32 v36, v2
	v_mov_b32_e32 v37, v2
	v_mov_b32_e32 v38, v2
	v_mov_b32_e32 v39, v2
	v_mov_b32_e32 v40, v2
	v_mov_b32_e32 v41, v2
	v_mov_b32_e32 v50, v2
	v_mov_b32_e32 v51, v2
	v_mov_b32_e32 v52, v2
	v_mov_b32_e32 v53, v2
	v_mov_b32_e32 v54, v2
	v_mov_b32_e32 v55, v2
	v_mov_b32_e32 v56, v2
	v_mov_b32_e32 v57, v2
	v_mov_b32_e32 v10, v2
	v_mov_b32_e32 v11, v2
	v_mov_b32_e32 v12, v2
	v_mov_b32_e32 v13, v2
	v_mov_b32_e32 v14, v2
	v_mov_b32_e32 v15, v2
	v_mov_b32_e32 v16, v2
	v_mov_b32_e32 v17, v2
	v_mov_b32_e32 v26, v2
	v_mov_b32_e32 v27, v2
	v_mov_b32_e32 v28, v2
	v_mov_b32_e32 v29, v2
	v_mov_b32_e32 v30, v2
	v_mov_b32_e32 v31, v2
	v_mov_b32_e32 v32, v2
	v_mov_b32_e32 v33, v2
	v_mov_b32_e32 v42, v2
	v_mov_b32_e32 v43, v2
	v_mov_b32_e32 v44, v2
	v_mov_b32_e32 v45, v2
	v_mov_b32_e32 v46, v2
	v_mov_b32_e32 v47, v2
	v_mov_b32_e32 v48, v2
	v_mov_b32_e32 v49, v2
	v_mov_b32_e32 v58, v2
	v_mov_b32_e32 v59, v2
	v_mov_b32_e32 v60, v2
	v_mov_b32_e32 v61, v2
	v_mov_b32_e32 v62, v2
	v_mov_b32_e32 v63, v2
	v_mov_b32_e32 v64, v2
	v_mov_b32_e32 v65, v2
	v_mov_b32_e32 v66, v2
	v_mov_b32_e32 v67, v2
	v_mov_b32_e32 v68, v2
	v_mov_b32_e32 v69, v2
	v_mov_b32_e32 v70, v2
	v_mov_b32_e32 v71, v2
	v_mov_b32_e32 v72, v2
	v_mov_b32_e32 v73, v2
	v_mov_b32_e32 v82, v2
	v_mov_b32_e32 v83, v2
	v_mov_b32_e32 v84, v2
	v_mov_b32_e32 v85, v2
	v_mov_b32_e32 v86, v2
	v_mov_b32_e32 v87, v2
	v_mov_b32_e32 v88, v2
	v_mov_b32_e32 v89, v2
	v_mov_b32_e32 v98, v2
	v_mov_b32_e32 v99, v2
	v_mov_b32_e32 v100, v2
	v_mov_b32_e32 v101, v2
	v_mov_b32_e32 v102, v2
	v_mov_b32_e32 v103, v2
	v_mov_b32_e32 v104, v2
	v_mov_b32_e32 v105, v2
	v_mov_b32_e32 v114, v2
	v_mov_b32_e32 v115, v2
	v_mov_b32_e32 v116, v2
	v_mov_b32_e32 v117, v2
	v_mov_b32_e32 v118, v2
	v_mov_b32_e32 v119, v2
	v_mov_b32_e32 v120, v2
	v_mov_b32_e32 v121, v2
	v_mov_b32_e32 v74, v2
	v_mov_b32_e32 v75, v2
	v_mov_b32_e32 v76, v2
	v_mov_b32_e32 v77, v2
	v_mov_b32_e32 v78, v2
	v_mov_b32_e32 v79, v2
	v_mov_b32_e32 v80, v2
	v_mov_b32_e32 v81, v2
	v_mov_b32_e32 v90, v2
	v_mov_b32_e32 v91, v2
	v_mov_b32_e32 v92, v2
	v_mov_b32_e32 v93, v2
	v_mov_b32_e32 v94, v2
	v_mov_b32_e32 v95, v2
	v_mov_b32_e32 v96, v2
	v_mov_b32_e32 v97, v2
	v_mov_b32_e32 v106, v2
	v_mov_b32_e32 v107, v2
	v_mov_b32_e32 v108, v2
	v_mov_b32_e32 v109, v2
	v_mov_b32_e32 v110, v2
	v_mov_b32_e32 v111, v2
	v_mov_b32_e32 v112, v2
	v_mov_b32_e32 v113, v2
	v_mov_b32_e32 v138, v2
	v_mov_b32_e32 v139, v2
	v_mov_b32_e32 v140, v2
	v_mov_b32_e32 v141, v2
	v_mov_b32_e32 v142, v2
	v_mov_b32_e32 v143, v2
	v_mov_b32_e32 v144, v2
	v_mov_b32_e32 v145, v2
	s_cmp_lt_u32 s42, 2
	s_cbranch_scc1 .Lp10_norestore
	s_andn2_b64 vcc, exec, s[6:7]
	s_cbranch_vccnz .Lp10_norestore
	s_barrier
